# baseline (speedup 1.0000x reference)
; __device__ __forceinline__ unsigned f2bf(float f) { unsigned u = __builtin_bit_cast(unsigned, f); return (u + 0x7fffu + ((u >> 16) & 1u)) >> 16; }
; __global__ void __launch_bounds__(NTHREADS, 2) fwd_kernel(Args args) {
;     ...
;         for (int i = gt; i < LN * LK; i += NT) { const int n = i / LK, k = i % LK, type = n >> 10, nn = n & 1023; float v = 0.f;
;             if (type == 0) { if (k < 64) v = ap->in[I_WDU][k * RW + nn]; } else if (type == 1) { if (k >= 64 && k < 128) v = ap->in[I_WAU][(k - 64) * RW + nn]; } else { if (k >= 128 && k < 288) v = ap->in[I_WGU][(k - 128) * RW + nn]; }
;             WLORA[i] = (bf16)f2bf(v); }
.LBB0_19:
	s_or_b64 exec, exec, s[6:7]
	s_mov_b32 s5, 0x120000
	v_cmp_gt_i32_e32 vcc, s5, v6
	s_and_saveexec_b64 s[6:7], vcc
	s_cbranch_execz .LBB0_38
	s_load_dwordx2 s[16:17], s[14:15], 0x90
	s_load_dwordx2 s[18:19], s[14:15], 0x88
	s_load_dwordx2 s[24:25], s[14:15], 0x78
	s_waitcnt lgkmcnt(0)
	s_add_u32 s26, s12, 0x6280000
	s_addc_u32 s27, s13, 0
	v_lshlrev_b32_e32 v1, 10, v6
	s_lshl_b32 s5, s4, 10
	s_mov_b64 s[28:29], 0
	s_mov_b32 s33, 0x2aaaaaab
	s_movk_i32 s35, 0x3ff
	s_movk_i32 s37, 0x400
	s_movk_i32 s42, 0xa0
	s_mov_b32 s43, 0xfffe0000
	v_mov_b32_e32 v3, 0
	s_mov_b32 s52, 0xffff0000
	s_movk_i32 s53, 0x7fff
	s_mov_b32 s54, 0x11ffff
	s_cmp_lg_u32 s4, 0x20000
	s_cbranch_scc1 .LBB0_22
	v_mov_b32_e32 v12, s24
	v_mov_b32_e32 v13, s25
	v_mov_b32_e32 v14, s18
	v_mov_b32_e32 v15, s19
	v_mov_b32_e32 v16, s16
	v_mov_b32_e32 v17, s17
	v_mov_b32_e32 v18, 64
	v_mov_b32_e32 v19, 0xa0
	v_mov_b32_e32 v3, 0
	v_mov_b32_e32 v49, 0
	v_mov_b32_e32 v20, v6
	v_mul_hi_u32 v40, v20, s33
	v_lshrrev_b32_e32 v41, 6, v40
	v_mul_u32_u24_e32 v40, 0x180, v41
	v_sub_u32_e32 v42, v20, v40
	v_lshrrev_b32_e32 v43, 10, v41
	v_and_b32_e32 v44, 0x3ff, v41
	v_lshlrev_b32_e32 v40, 6, v43
	v_cmp_eq_u32_e32 vcc, 2, v43
	v_sub_u32_e32 v45, v42, v40
	s_nop 0
	v_cndmask_b32_e32 v46, v18, v19, vcc
	v_cmp_eq_u32_e64 s[44:45], 0, v43
	v_cmp_lt_u32_e32 vcc, v45, v46
	s_nop 1
	v_cndmask_b32_e64 v29, 0, 1, vcc
	v_cndmask_b32_e32 v45, v3, v45, vcc
	v_cndmask_b32_e64 v50, v14, v12, s[44:45]
	v_cndmask_b32_e64 v51, v15, v13, s[44:45]
	v_cmp_eq_u32_e32 vcc, 2, v43
	v_lshl_add_u32 v48, v45, 10, v44
	s_nop 0
	v_cndmask_b32_e32 v50, v50, v16, vcc
	v_cndmask_b32_e32 v51, v51, v17, vcc
	v_lshl_add_u64 v[52:53], v[48:49], 2, v[50:51]
	global_load_dword v54, v[52:53], off
	v_add_u32_e32 v21, 0x20000, v20
	v_mul_hi_u32 v40, v21, s33
	v_lshrrev_b32_e32 v41, 6, v40
	v_mul_u32_u24_e32 v40, 0x180, v41
	v_sub_u32_e32 v42, v21, v40
	v_lshrrev_b32_e32 v43, 10, v41
	v_and_b32_e32 v44, 0x3ff, v41
	v_lshlrev_b32_e32 v40, 6, v43
	v_cmp_eq_u32_e32 vcc, 2, v43
	v_sub_u32_e32 v45, v42, v40
	s_nop 0
	v_cndmask_b32_e32 v46, v18, v19, vcc
	v_cmp_eq_u32_e64 s[44:45], 0, v43
	v_cmp_lt_u32_e32 vcc, v45, v46
	s_nop 1
	v_cndmask_b32_e64 v30, 0, 1, vcc
	v_cndmask_b32_e32 v45, v3, v45, vcc
	v_cndmask_b32_e64 v50, v14, v12, s[44:45]
	v_cndmask_b32_e64 v51, v15, v13, s[44:45]
	v_cmp_eq_u32_e32 vcc, 2, v43
	v_lshl_add_u32 v48, v45, 10, v44
	s_nop 0
	v_cndmask_b32_e32 v50, v50, v16, vcc
	v_cndmask_b32_e32 v51, v51, v17, vcc
	v_lshl_add_u64 v[52:53], v[48:49], 2, v[50:51]
	global_load_dword v55, v[52:53], off
	v_add_u32_e32 v22, 0x20000, v21
	v_mul_hi_u32 v40, v22, s33
	v_lshrrev_b32_e32 v41, 6, v40
	v_mul_u32_u24_e32 v40, 0x180, v41
	v_sub_u32_e32 v42, v22, v40
	v_lshrrev_b32_e32 v43, 10, v41
	v_and_b32_e32 v44, 0x3ff, v41
	v_lshlrev_b32_e32 v40, 6, v43
	v_cmp_eq_u32_e32 vcc, 2, v43
	v_sub_u32_e32 v45, v42, v40
	s_nop 0
	v_cndmask_b32_e32 v46, v18, v19, vcc
	v_cmp_eq_u32_e64 s[44:45], 0, v43
	v_cmp_lt_u32_e32 vcc, v45, v46
	s_nop 1
	v_cndmask_b32_e64 v31, 0, 1, vcc
	v_cndmask_b32_e32 v45, v3, v45, vcc
	v_cndmask_b32_e64 v50, v14, v12, s[44:45]
	v_cndmask_b32_e64 v51, v15, v13, s[44:45]
	v_cmp_eq_u32_e32 vcc, 2, v43
	v_lshl_add_u32 v48, v45, 10, v44
	s_nop 0
	v_cndmask_b32_e32 v50, v50, v16, vcc
	v_cndmask_b32_e32 v51, v51, v17, vcc
	v_lshl_add_u64 v[52:53], v[48:49], 2, v[50:51]
	global_load_dword v56, v[52:53], off
	v_add_u32_e32 v23, 0x20000, v22
	v_mul_hi_u32 v40, v23, s33
	v_lshrrev_b32_e32 v41, 6, v40
	v_mul_u32_u24_e32 v40, 0x180, v41
	v_sub_u32_e32 v42, v23, v40
	v_lshrrev_b32_e32 v43, 10, v41
	v_and_b32_e32 v44, 0x3ff, v41
	v_lshlrev_b32_e32 v40, 6, v43
	v_cmp_eq_u32_e32 vcc, 2, v43
	v_sub_u32_e32 v45, v42, v40
	s_nop 0
	v_cndmask_b32_e32 v46, v18, v19, vcc
	v_cmp_eq_u32_e64 s[44:45], 0, v43
	v_cmp_lt_u32_e32 vcc, v45, v46
	s_nop 1
	v_cndmask_b32_e64 v32, 0, 1, vcc
	v_cndmask_b32_e32 v45, v3, v45, vcc
	v_cndmask_b32_e64 v50, v14, v12, s[44:45]
	v_cndmask_b32_e64 v51, v15, v13, s[44:45]
	v_cmp_eq_u32_e32 vcc, 2, v43
	v_lshl_add_u32 v48, v45, 10, v44
	s_nop 0
	v_cndmask_b32_e32 v50, v50, v16, vcc
	v_cndmask_b32_e32 v51, v51, v17, vcc
	v_lshl_add_u64 v[52:53], v[48:49], 2, v[50:51]
	global_load_dword v57, v[52:53], off
	v_add_u32_e32 v24, 0x20000, v23
	v_mul_hi_u32 v40, v24, s33
	v_lshrrev_b32_e32 v41, 6, v40
	v_mul_u32_u24_e32 v40, 0x180, v41
	v_sub_u32_e32 v42, v24, v40
	v_lshrrev_b32_e32 v43, 10, v41
	v_and_b32_e32 v44, 0x3ff, v41
	v_lshlrev_b32_e32 v40, 6, v43
	v_cmp_eq_u32_e32 vcc, 2, v43
	v_sub_u32_e32 v45, v42, v40
	s_nop 0
	v_cndmask_b32_e32 v46, v18, v19, vcc
	v_cmp_eq_u32_e64 s[44:45], 0, v43
	v_cmp_lt_u32_e32 vcc, v45, v46
	s_nop 1
	v_cndmask_b32_e64 v33, 0, 1, vcc
	v_cndmask_b32_e32 v45, v3, v45, vcc
	v_cndmask_b32_e64 v50, v14, v12, s[44:45]
	v_cndmask_b32_e64 v51, v15, v13, s[44:45]
	v_cmp_eq_u32_e32 vcc, 2, v43
	v_lshl_add_u32 v48, v45, 10, v44
	s_nop 0
	v_cndmask_b32_e32 v50, v50, v16, vcc
	v_cndmask_b32_e32 v51, v51, v17, vcc
	v_lshl_add_u64 v[52:53], v[48:49], 2, v[50:51]
	global_load_dword v58, v[52:53], off
	v_add_u32_e32 v25, 0x20000, v24
	v_mul_hi_u32 v40, v25, s33
	v_lshrrev_b32_e32 v41, 6, v40
	v_mul_u32_u24_e32 v40, 0x180, v41
	v_sub_u32_e32 v42, v25, v40
	v_lshrrev_b32_e32 v43, 10, v41
	v_and_b32_e32 v44, 0x3ff, v41
	v_lshlrev_b32_e32 v40, 6, v43
; __device__ __forceinline__ unsigned f2bf(float f) { unsigned u = __builtin_bit_cast(unsigned, f); return (u + 0x7fffu + ((u >> 16) & 1u)) >> 16; }
; __global__ void __launch_bounds__(NTHREADS, 2) fwd_kernel(Args args) {
;     ...
;         for (int i = gt; i < LN * LK; i += NT) { const int n = i / LK, k = i % LK, type = n >> 10, nn = n & 1023; float v = 0.f;
;             if (type == 0) { if (k < 64) v = ap->in[I_WDU][k * RW + nn]; } else if (type == 1) { if (k >= 64 && k < 128) v = ap->in[I_WAU][(k - 64) * RW + nn]; } else { if (k >= 128 && k < 288) v = ap->in[I_WGU][(k - 128) * RW + nn]; }
;             WLORA[i] = (bf16)f2bf(v); }
	v_cmp_eq_u32_e32 vcc, 2, v43
	v_sub_u32_e32 v45, v42, v40
	s_nop 0
	v_cndmask_b32_e32 v46, v18, v19, vcc
	v_cmp_eq_u32_e64 s[44:45], 0, v43
	v_cmp_lt_u32_e32 vcc, v45, v46
	s_nop 1
	v_cndmask_b32_e64 v34, 0, 1, vcc
	v_cndmask_b32_e32 v45, v3, v45, vcc
	v_cndmask_b32_e64 v50, v14, v12, s[44:45]
	v_cndmask_b32_e64 v51, v15, v13, s[44:45]
	v_cmp_eq_u32_e32 vcc, 2, v43
	v_lshl_add_u32 v48, v45, 10, v44
	s_nop 0
	v_cndmask_b32_e32 v50, v50, v16, vcc
	v_cndmask_b32_e32 v51, v51, v17, vcc
	v_lshl_add_u64 v[52:53], v[48:49], 2, v[50:51]
	global_load_dword v59, v[52:53], off
	v_add_u32_e32 v26, 0x20000, v25
	v_mul_hi_u32 v40, v26, s33
	v_lshrrev_b32_e32 v41, 6, v40
	v_mul_u32_u24_e32 v40, 0x180, v41
	v_sub_u32_e32 v42, v26, v40
	v_lshrrev_b32_e32 v43, 10, v41
	v_and_b32_e32 v44, 0x3ff, v41
	v_lshlrev_b32_e32 v40, 6, v43
	v_cmp_eq_u32_e32 vcc, 2, v43
	v_sub_u32_e32 v45, v42, v40
	s_nop 0
	v_cndmask_b32_e32 v46, v18, v19, vcc
	v_cmp_eq_u32_e64 s[44:45], 0, v43
	v_cmp_lt_u32_e32 vcc, v45, v46
	s_nop 1
	v_cndmask_b32_e64 v35, 0, 1, vcc
	v_cndmask_b32_e32 v45, v3, v45, vcc
	v_cndmask_b32_e64 v50, v14, v12, s[44:45]
	v_cndmask_b32_e64 v51, v15, v13, s[44:45]
	v_cmp_eq_u32_e32 vcc, 2, v43
	v_lshl_add_u32 v48, v45, 10, v44
	s_nop 0
	v_cndmask_b32_e32 v50, v50, v16, vcc
	v_cndmask_b32_e32 v51, v51, v17, vcc
	v_lshl_add_u64 v[52:53], v[48:49], 2, v[50:51]
	global_load_dword v60, v[52:53], off
	v_add_u32_e32 v27, 0x20000, v26
	v_mul_hi_u32 v40, v27, s33
	v_lshrrev_b32_e32 v41, 6, v40
	v_mul_u32_u24_e32 v40, 0x180, v41
	v_sub_u32_e32 v42, v27, v40
	v_lshrrev_b32_e32 v43, 10, v41
	v_and_b32_e32 v44, 0x3ff, v41
	v_lshlrev_b32_e32 v40, 6, v43
	v_cmp_eq_u32_e32 vcc, 2, v43
	v_sub_u32_e32 v45, v42, v40
	s_nop 0
	v_cndmask_b32_e32 v46, v18, v19, vcc
	v_cmp_eq_u32_e64 s[44:45], 0, v43
	v_cmp_lt_u32_e32 vcc, v45, v46
	s_nop 1
	v_cndmask_b32_e64 v36, 0, 1, vcc
	v_cndmask_b32_e32 v45, v3, v45, vcc
	v_cndmask_b32_e64 v50, v14, v12, s[44:45]
	v_cndmask_b32_e64 v51, v15, v13, s[44:45]
	v_cmp_eq_u32_e32 vcc, 2, v43
	v_lshl_add_u32 v48, v45, 10, v44
	s_nop 0
	v_cndmask_b32_e32 v50, v50, v16, vcc
	v_cndmask_b32_e32 v51, v51, v17, vcc
	v_lshl_add_u64 v[52:53], v[48:49], 2, v[50:51]
	global_load_dword v61, v[52:53], off
	v_add_u32_e32 v28, 0x20000, v27
	v_mul_hi_u32 v40, v28, s33
	v_lshrrev_b32_e32 v41, 6, v40
	v_mul_u32_u24_e32 v40, 0x180, v41
	v_sub_u32_e32 v42, v28, v40
	v_lshrrev_b32_e32 v43, 10, v41
	v_and_b32_e32 v44, 0x3ff, v41
	v_lshlrev_b32_e32 v40, 6, v43
	v_cmp_eq_u32_e32 vcc, 2, v43
	v_sub_u32_e32 v45, v42, v40
	s_nop 0
	v_cndmask_b32_e32 v46, v18, v19, vcc
	v_cmp_eq_u32_e64 s[44:45], 0, v43
	v_cmp_lt_u32_e32 vcc, v45, v46
	s_nop 1
	v_cndmask_b32_e64 v37, 0, 1, vcc
	v_cndmask_b32_e32 v45, v3, v45, vcc
	v_cndmask_b32_e64 v50, v14, v12, s[44:45]
	v_cndmask_b32_e64 v51, v15, v13, s[44:45]
	v_cmp_eq_u32_e32 vcc, 2, v43
	v_lshl_add_u32 v48, v45, 10, v44
	s_nop 0
	v_cndmask_b32_e32 v50, v50, v16, vcc
	v_cndmask_b32_e32 v51, v51, v17, vcc
	v_lshl_add_u64 v[52:53], v[48:49], 2, v[50:51]
	global_load_dword v62, v[52:53], off
	s_waitcnt vmcnt(0)
	v_cmp_ne_u32_e32 vcc, 0, v29
	v_mov_b32_e32 v48, v20
	v_lshl_add_u64 v[52:53], v[48:49], 1, s[26:27]
	v_cndmask_b32_e32 v54, v3, v54, vcc
	v_bfe_u32 v40, v54, 16, 1
	v_add3_u32 v54, v54, v40, s53
	global_store_short_d16_hi v[52:53], v54, off
	v_cmp_ne_u32_e32 vcc, 0, v30
	v_mov_b32_e32 v48, v21
	v_lshl_add_u64 v[52:53], v[48:49], 1, s[26:27]
	v_cndmask_b32_e32 v55, v3, v55, vcc
	v_bfe_u32 v40, v55, 16, 1
	v_add3_u32 v55, v55, v40, s53
	global_store_short_d16_hi v[52:53], v55, off
	v_cmp_ne_u32_e32 vcc, 0, v31
	v_mov_b32_e32 v48, v22
	v_lshl_add_u64 v[52:53], v[48:49], 1, s[26:27]
	v_cndmask_b32_e32 v56, v3, v56, vcc
	v_bfe_u32 v40, v56, 16, 1
	v_add3_u32 v56, v56, v40, s53
	global_store_short_d16_hi v[52:53], v56, off
	v_cmp_ne_u32_e32 vcc, 0, v32
	v_mov_b32_e32 v48, v23
	v_lshl_add_u64 v[52:53], v[48:49], 1, s[26:27]
	v_cndmask_b32_e32 v57, v3, v57, vcc
	v_bfe_u32 v40, v57, 16, 1
	v_add3_u32 v57, v57, v40, s53
	global_store_short_d16_hi v[52:53], v57, off
	v_cmp_ne_u32_e32 vcc, 0, v33
	v_mov_b32_e32 v48, v24
	v_lshl_add_u64 v[52:53], v[48:49], 1, s[26:27]
	v_cndmask_b32_e32 v58, v3, v58, vcc
	v_bfe_u32 v40, v58, 16, 1
	v_add3_u32 v58, v58, v40, s53
	global_store_short_d16_hi v[52:53], v58, off
	v_cmp_ne_u32_e32 vcc, 0, v34
	v_mov_b32_e32 v48, v25
	v_lshl_add_u64 v[52:53], v[48:49], 1, s[26:27]
	v_cndmask_b32_e32 v59, v3, v59, vcc
	v_bfe_u32 v40, v59, 16, 1
	v_add3_u32 v59, v59, v40, s53
	global_store_short_d16_hi v[52:53], v59, off
	v_cmp_ne_u32_e32 vcc, 0, v35
	v_mov_b32_e32 v48, v26
	v_lshl_add_u64 v[52:53], v[48:49], 1, s[26:27]
	v_cndmask_b32_e32 v60, v3, v60, vcc
	v_bfe_u32 v40, v60, 16, 1
	v_add3_u32 v60, v60, v40, s53
	global_store_short_d16_hi v[52:53], v60, off
	v_cmp_ne_u32_e32 vcc, 0, v36
	v_mov_b32_e32 v48, v27
	v_lshl_add_u64 v[52:53], v[48:49], 1, s[26:27]
	v_cndmask_b32_e32 v61, v3, v61, vcc
	v_bfe_u32 v40, v61, 16, 1
	v_add3_u32 v61, v61, v40, s53
	global_store_short_d16_hi v[52:53], v61, off
	v_cmp_ne_u32_e32 vcc, 0, v37
	v_mov_b32_e32 v48, v28
	v_lshl_add_u64 v[52:53], v[48:49], 1, s[26:27]
	v_cndmask_b32_e32 v62, v3, v62, vcc
	v_bfe_u32 v40, v62, 16, 1
	v_add3_u32 v62, v62, v40, s53
	global_store_short_d16_hi v[52:53], v62, off
	s_branch .LBB0_38
	s_branch .LBB0_22

; template <int MODE> __device__ __forceinline__ void row_phase(const float* xp, const float* xs, const bf16* fb, const bf16* fsp  , float scale, const float* g_post, const float* g_next, float* out, bf16* A, const bf16* rb  , bf16* hb  , int gw, int NGW, int lane) {
;     f32x4 gp[8], gn[8];
; #pragma unroll
;     for (int j = 0; j < 8; ++j) { if (MODE != 0) gp[j] = *(const f32x4*)(g_post + RP_COL(j)); if (MODE != 2) gn[j] = *(const f32x4*)(g_next + RP_COL(j)); }
;     for (int m = gw; m < M; m += NGW) {
;         f32x4 h[8];
;         if (MODE == 0 || rb == nullptr) { const float* rp = xrow_ptr(xp, xs, m);
; #pragma unroll
;             for (int j = 0; j < 8; ++j) h[j] = *(const f32x4*)(rp + RP_COL(j)); }
.LBB0_38:
	s_or_b64 exec, exec, s[6:7]
	s_cmpk_gt_i32 s34, 0x43ff
	s_cbranch_scc1 .LBB0_41
	s_load_dwordx2 s[4:5], s[14:15], 0x28
	v_lshlrev_b32_e32 v34, 3, v166
	v_lshlrev_b32_e32 v1, 5, v166
	v_or_b32_e32 v36, 0x400, v34
	v_or_b32_e32 v38, 0x600, v34
	s_waitcnt lgkmcnt(0)
	global_load_dwordx4 v[2:5], v1, s[4:5] offset:16
	global_load_dwordx4 v[6:9], v1, s[4:5]
	global_load_dwordx4 v[10:13], v1, s[4:5] offset:2064
	global_load_dwordx4 v[14:17], v1, s[4:5] offset:2048
	v_lshlrev_b32_e32 v1, 2, v36
	global_load_dwordx4 v[18:21], v1, s[4:5] offset:16
	global_load_dwordx4 v[22:25], v1, s[4:5]
	v_lshlrev_b32_e32 v1, 2, v38
	global_load_dwordx4 v[26:29], v1, s[4:5] offset:16
	global_load_dwordx4 v[30:33], v1, s[4:5]
	v_mbcnt_lo_u32_b32 v1, -1, 0
	v_mbcnt_hi_u32_b32 v35, -1, v1
	v_and_b32_e32 v37, 64, v35
	s_ashr_i32 s35, s34, 31
	s_sub_i32 s100, s36, s34
	s_add_i32 s100, s100, -1
	s_mov_b32 s101, 0
	s_load_dwordx4 s[4:7], s[14:15], 0x0
	v_xor_b32_e32 v1, 16, v35
	v_add_u32_e32 v37, 64, v37
	s_lshl_b64 s[14:15], s[100:101], 12
	v_cmp_lt_i32_e32 vcc, v1, v37
	v_xor_b32_e32 v39, 32, v35
	s_add_u32 s12, s12, s14
	v_mov_b32_e32 v41, 0
	v_cndmask_b32_e32 v1, v35, v1, vcc
	v_cmp_lt_i32_e32 vcc, v39, v37
	v_lshlrev_b32_e32 v40, 4, v166
	s_addc_u32 s13, s13, s15
	v_cndmask_b32_e32 v35, v35, v39, vcc
	v_lshl_add_u64 v[40:41], s[12:13], 0, v[40:41]
	s_mov_b64 s[12:13], 0x64c0000
	s_ashr_i32 s37, s36, 31
	v_lshlrev_b32_e32 v1, 2, v1
	v_lshlrev_b32_e32 v68, 2, v35
	v_lshl_add_u64 v[66:67], v[40:41], 0, s[12:13]
	s_lshl_b64 s[12:13], s[36:37], 12
	v_lshlrev_b32_e32 v69, 2, v34
	v_lshlrev_b32_e32 v70, 2, v36
	v_lshlrev_b32_e32 v71, 2, v38
	v_mov_b32_e32 v72, 0x358637bd
	s_mov_b64 s[14:15], s[100:101]

; __global__ void __launch_bounds__(NTHREADS, 2) fwd_kernel(Args args) {
	.amdhsa_kernel _Z10fwd_kernel4Args
		.amdhsa_group_segment_fixed_size 0
		.amdhsa_private_segment_fixed_size 0
		.amdhsa_kernarg_size 528
		.amdhsa_user_sgpr_count 2
		.amdhsa_user_sgpr_dispatch_ptr 0
		.amdhsa_user_sgpr_queue_ptr 0
		.amdhsa_user_sgpr_kernarg_segment_ptr 1
		.amdhsa_user_sgpr_dispatch_id 0
		.amdhsa_user_sgpr_kernarg_preload_length 0
		.amdhsa_user_sgpr_kernarg_preload_offset 0
		.amdhsa_user_sgpr_private_segment_size 0
		.amdhsa_uses_dynamic_stack 0
		.amdhsa_enable_private_segment 0
		.amdhsa_system_sgpr_workgroup_id_x 1
		.amdhsa_system_sgpr_workgroup_id_y 0
		.amdhsa_system_sgpr_workgroup_id_z 0
		.amdhsa_system_sgpr_workgroup_info 0
		.amdhsa_system_vgpr_workitem_id 2
		.amdhsa_next_free_vgpr 233
		.amdhsa_next_free_sgpr 102
		.amdhsa_accum_offset 236
		.amdhsa_reserve_vcc 1
		.amdhsa_float_round_mode_32 0
		.amdhsa_float_round_mode_16_64 0
		.amdhsa_float_denorm_mode_32 3
		.amdhsa_float_denorm_mode_16_64 3
		.amdhsa_dx10_clamp 1
		.amdhsa_ieee_mode 1
		.amdhsa_fp16_overflow 0
		.amdhsa_tg_split 0
		.amdhsa_exception_fp_ieee_invalid_op 0
		.amdhsa_exception_fp_denorm_src 0
		.amdhsa_exception_fp_ieee_div_zero 0
		.amdhsa_exception_fp_ieee_overflow 0
		.amdhsa_exception_fp_ieee_underflow 0
		.amdhsa_exception_fp_ieee_inexact 0
		.amdhsa_exception_int_div_zero 0
	.end_amdhsa_kernel

; __global__ void __launch_bounds__(NTHREADS, 2) fwd_kernel(Args args) {
amdhsa.kernels:
  - .agpr_count:     0
    .args:
      - .offset:         0
        .size:           272
        .value_kind:     by_value
      - .offset:         272
        .size:           4
        .value_kind:     hidden_block_count_x
      - .offset:         276
        .size:           4
        .value_kind:     hidden_block_count_y
      - .offset:         280
        .size:           4
        .value_kind:     hidden_block_count_z
      - .offset:         284
        .size:           2
        .value_kind:     hidden_group_size_x
      - .offset:         286
        .size:           2
        .value_kind:     hidden_group_size_y
      - .offset:         288
        .size:           2
        .value_kind:     hidden_group_size_z
      - .offset:         290
        .size:           2
        .value_kind:     hidden_remainder_x
      - .offset:         292
        .size:           2
        .value_kind:     hidden_remainder_y
      - .offset:         294
        .size:           2
        .value_kind:     hidden_remainder_z
      - .offset:         312
        .size:           8
        .value_kind:     hidden_global_offset_x
      - .offset:         320
        .size:           8
        .value_kind:     hidden_global_offset_y
      - .offset:         328
        .size:           8
        .value_kind:     hidden_global_offset_z
      - .offset:         336
        .size:           2
        .value_kind:     hidden_grid_dims
      - .offset:         360
        .size:           8
        .value_kind:     hidden_multigrid_sync_arg
      - .offset:         392
        .size:           4
        .value_kind:     hidden_dynamic_lds_size
    .group_segment_fixed_size: 0
    .kernarg_segment_align: 8
    .kernarg_segment_size: 528
    .language:       OpenCL C
    .language_version:
      - 2
      - 0
    .max_flat_workgroup_size: 512
    .name:           _Z10fwd_kernel4Args
    .private_segment_fixed_size: 0
    .sgpr_count:     108
    .sgpr_spill_count: 5
    .symbol:         _Z10fwd_kernel4Args.kd
    .uniform_work_group_size: 1
    .uses_dynamic_stack: false
    .vgpr_count:     233
    .vgpr_spill_count: 0
    .wavefront_size: 64
